# GEMM mainloop: hipcc's 31 per-phase s_setprio flips deleted, one static s_setprio 1 for waves 4-7 before the K loop, reset to 0 after the tail (timing-only, bit-identical)
# speedup vs baseline: 1.0170x; 1.0021x over previous
; #define WAIT_V(n) asm volatile("s_waitcnt vmcnt(" #n ")" ::: "memory")
; #define BAR __builtin_amdgcn_s_barrier()
; DI void gemm_tile(const GD& g, int pm, int pn, bf16_t* shm) {
;     ...
;   f32x4 acc[2][2][4][2] = {};
;   bf16x8 At[4][2], B0[2][2], B1[2][2];
;   const int nt = g.K / BK;
;   STAGE(SB(0, 0), Bt, ldb, bh0, 0); STAGE(SA(0, 0), A, lda, brow, 0);
;   STAGE(SB(0, 1), Bt, ldb, bh1, 0); STAGE(SA(0, 1), A, lda, brow + HALF, 0);
;   if (wr == 1) BAR;
;   WAIT_V(4); BAR;
;   STAGE(SB(1, 0), Bt, ldb, bh0, 1); STAGE(SA(1, 0), A, lda, brow, 1); STAGE(SB(1, 1), Bt, ldb, bh1, 1);
;   WAIT_V(6); BAR;
.LBB0_458:
	v_lshlrev_b32_e32 v2, 2, v130
	v_and_b32_e32 v2, 32, v2
	v_bitop3_b32 v132, v151, v2, v150 bitop3:0x36
	v_mov_b32_e32 v117, 0
	s_andn2_b64 vcc, exec, s[2:3]
	v_readlane_b32 s2, v253, 33
	s_lshr_b32 s24, s67, 6
	v_mov_b32_e32 v116, v117
	v_add_u32_e32 v141, s2, v132
	v_mov_b32_e32 v115, v117
	v_mov_b32_e32 v114, v117
	v_mov_b32_e32 v129, v117
	v_mov_b32_e32 v128, v117
	v_mov_b32_e32 v127, v117
	v_mov_b32_e32 v126, v117
	v_mov_b32_e32 v125, v117
	v_mov_b32_e32 v124, v117
	v_mov_b32_e32 v123, v117
	v_mov_b32_e32 v122, v117
	v_mov_b32_e32 v121, v117
	v_mov_b32_e32 v120, v117
	v_mov_b32_e32 v119, v117
	v_mov_b32_e32 v118, v117
	v_mov_b32_e32 v113, v117
	v_mov_b32_e32 v112, v117
	v_mov_b32_e32 v111, v117
	v_mov_b32_e32 v110, v117
	v_mov_b32_e32 v109, v117
	v_mov_b32_e32 v108, v117
	v_mov_b32_e32 v107, v117
	v_mov_b32_e32 v106, v117
	v_mov_b32_e32 v105, v117
	v_mov_b32_e32 v104, v117
	v_mov_b32_e32 v103, v117
	v_mov_b32_e32 v102, v117
	v_mov_b32_e32 v101, v117
	v_mov_b32_e32 v100, v117
	v_mov_b32_e32 v99, v117
	v_mov_b32_e32 v98, v117
	v_mov_b32_e32 v97, v117
	v_mov_b32_e32 v96, v117
	v_mov_b32_e32 v95, v117
	v_mov_b32_e32 v94, v117
	v_mov_b32_e32 v93, v117
	v_mov_b32_e32 v92, v117
	v_mov_b32_e32 v91, v117
	v_mov_b32_e32 v90, v117
	v_mov_b32_e32 v89, v117
	v_mov_b32_e32 v88, v117
	v_mov_b32_e32 v87, v117
	v_mov_b32_e32 v86, v117
	v_mov_b32_e32 v85, v117
	v_mov_b32_e32 v84, v117
	v_mov_b32_e32 v83, v117
	v_mov_b32_e32 v82, v117
	v_mov_b32_e32 v81, v117
	v_mov_b32_e32 v80, v117
	v_mov_b32_e32 v79, v117
	v_mov_b32_e32 v78, v117
	v_mov_b32_e32 v77, v117
	v_mov_b32_e32 v76, v117
	v_mov_b32_e32 v75, v117
	v_mov_b32_e32 v74, v117
	v_mov_b32_e32 v73, v117
	v_mov_b32_e32 v72, v117
	v_mov_b32_e32 v71, v117
	v_mov_b32_e32 v70, v117
	v_mov_b32_e32 v69, v117
	v_mov_b32_e32 v68, v117
	v_mov_b32_e32 v67, v117
	v_mov_b32_e32 v66, v117
	v_mov_b32_e32 v65, v117
	v_mov_b32_e32 v64, v117
	v_mov_b32_e32 v63, v117
	v_mov_b32_e32 v62, v117
	v_mov_b32_e32 v61, v117
	v_mov_b32_e32 v60, v117
	v_mov_b32_e32 v59, v117
	v_mov_b32_e32 v58, v117
	v_mov_b32_e32 v57, v117
	v_mov_b32_e32 v56, v117
	v_mov_b32_e32 v55, v117
	v_mov_b32_e32 v54, v117
	v_mov_b32_e32 v53, v117
	v_mov_b32_e32 v52, v117
	v_mov_b32_e32 v51, v117
	v_mov_b32_e32 v50, v117
	v_mov_b32_e32 v49, v117
	v_mov_b32_e32 v48, v117
	v_mov_b32_e32 v47, v117
	v_mov_b32_e32 v46, v117
	v_mov_b32_e32 v45, v117
	v_mov_b32_e32 v44, v117
	v_mov_b32_e32 v43, v117
	v_mov_b32_e32 v42, v117
	v_mov_b32_e32 v41, v117
	v_mov_b32_e32 v40, v117
	v_mov_b32_e32 v39, v117
	v_mov_b32_e32 v38, v117
	s_waitcnt vmcnt(0)
	v_mov_b32_e32 v37, v117
	v_mov_b32_e32 v36, v117
	v_mov_b32_e32 v35, v117
	v_mov_b32_e32 v34, v117
	v_mov_b32_e32 v33, v117
	v_mov_b32_e32 v32, v117
	v_mov_b32_e32 v31, v117
	v_mov_b32_e32 v30, v117
	v_mov_b32_e32 v29, v117
	v_mov_b32_e32 v28, v117
	v_mov_b32_e32 v27, v117
	v_mov_b32_e32 v26, v117
	v_mov_b32_e32 v25, v117
	v_mov_b32_e32 v24, v117
	v_mov_b32_e32 v23, v117
	v_mov_b32_e32 v22, v117
	v_mov_b32_e32 v21, v117
	v_mov_b32_e32 v20, v117
	v_mov_b32_e32 v19, v117
	v_mov_b32_e32 v18, v117
	v_mov_b32_e32 v17, v117
	v_mov_b32_e32 v16, v117
	v_mov_b32_e32 v15, v117
	v_mov_b32_e32 v14, v117
	v_mov_b32_e32 v13, v117
	v_mov_b32_e32 v12, v117
	v_mov_b32_e32 v11, v117
	v_mov_b32_e32 v10, v117
	v_mov_b32_e32 v9, v117
	v_mov_b32_e32 v8, v117
	v_mov_b32_e32 v7, v117
	v_mov_b32_e32 v6, v117
	v_mov_b32_e32 v5, v117
	v_mov_b32_e32 v4, v117
	v_mov_b32_e32 v3, v117
	v_mov_b32_e32 v2, v117
	s_cbranch_vccnz .LBB0_462
	s_add_i32 s3, 0, 0x14000
	v_add_u32_e32 v3, s3, v132
	s_add_i32 s3, 0, 0x18000
	v_add_u32_e32 v4, s3, v132
	s_add_i32 s3, 0, 0x1c000
	v_bitop3_b32 v133, v151, v152, v150 bitop3:0x36
	v_add_u32_e32 v5, s3, v132
	v_add_u32_e32 v146, 0, v133
	v_or_b32_e32 v135, 0x800, v142
	v_or_b32_e32 v137, 0x1000, v142
	v_or_b32_e32 v139, 0x1800, v142
	v_mov_b32_e32 v2, 0
	s_add_i32 s2, s24, -2
	v_or_b32_e32 v134, 0x400, v142
	v_or_b32_e32 v136, 0xc00, v142
	v_or_b32_e32 v138, 0x1400, v142
	v_or_b32_e32 v140, 0x1c00, v142
	s_mov_b32 s3, 0
	v_add_u32_e32 v147, v141, v131
	v_add_u32_e32 v148, v146, v135
	v_add_u32_e32 v149, v146, v137
	v_add_u32_e32 v150, v146, v139
	v_add_u32_e32 v151, v3, v131
	v_add_u32_e32 v152, v4, v131
	v_add_u32_e32 v153, v5, v131
	v_mov_b32_e32 v3, v2
	v_mov_b32_e32 v4, v2
	v_mov_b32_e32 v5, v2
	v_mov_b32_e32 v6, v2
	v_mov_b32_e32 v7, v2
	v_mov_b32_e32 v8, v2
	v_mov_b32_e32 v9, v2
	v_mov_b32_e32 v10, v2
	v_mov_b32_e32 v11, v2
	v_mov_b32_e32 v12, v2
	v_mov_b32_e32 v13, v2
	v_mov_b32_e32 v14, v2
	v_mov_b32_e32 v15, v2
	v_mov_b32_e32 v16, v2
	v_mov_b32_e32 v17, v2
	v_mov_b32_e32 v18, v2
	v_mov_b32_e32 v19, v2
	v_mov_b32_e32 v20, v2
	v_mov_b32_e32 v21, v2
	v_mov_b32_e32 v22, v2
	v_mov_b32_e32 v23, v2
	v_mov_b32_e32 v24, v2
	v_mov_b32_e32 v25, v2
	v_mov_b32_e32 v26, v2
	v_mov_b32_e32 v27, v2
	v_mov_b32_e32 v28, v2
	v_mov_b32_e32 v29, v2
	v_mov_b32_e32 v30, v2
	v_mov_b32_e32 v31, v2
	v_mov_b32_e32 v32, v2
	v_mov_b32_e32 v33, v2
	v_mov_b32_e32 v34, v2
	v_mov_b32_e32 v35, v2
	v_mov_b32_e32 v36, v2
	v_mov_b32_e32 v37, v2
	v_mov_b32_e32 v38, v2
	v_mov_b32_e32 v39, v2
	v_mov_b32_e32 v40, v2
	v_mov_b32_e32 v41, v2
	v_mov_b32_e32 v42, v2
	v_mov_b32_e32 v43, v2
	v_mov_b32_e32 v44, v2
	v_mov_b32_e32 v45, v2
	v_mov_b32_e32 v46, v2
	v_mov_b32_e32 v47, v2
	v_mov_b32_e32 v48, v2
	v_mov_b32_e32 v49, v2
	v_mov_b32_e32 v50, v2
	v_mov_b32_e32 v51, v2
	v_mov_b32_e32 v52, v2
	v_mov_b32_e32 v53, v2
	v_mov_b32_e32 v54, v2
	v_mov_b32_e32 v55, v2
	v_mov_b32_e32 v56, v2
	v_mov_b32_e32 v57, v2
	v_mov_b32_e32 v58, v2
	v_mov_b32_e32 v59, v2
	v_mov_b32_e32 v60, v2
	v_mov_b32_e32 v61, v2
	v_mov_b32_e32 v62, v2
	v_mov_b32_e32 v63, v2
; #define LDA(dst, b, h) _Pragma("unroll") for (int m = 0; m < 4; ++m) _Pragma("unroll") for (int k = 0; k < 2; ++k) \
;     dst[m][k] = *reinterpret_cast<const bf16x8*>((char*)SA(b, h) + lds_byte(wr * 64 + m * 16 + fr, k * 32 + fq * 8))
; #define LDB(dst, b, h) _Pragma("unroll") for (int n = 0; n < 2; ++n) _Pragma("unroll") for (int k = 0; k < 2; ++k) \
;     dst[n][k] = *reinterpret_cast<const bf16x8*>((char*)SB(b, h) + lds_byte(wc * 32 + n * 16 + fr, k * 32 + fq * 8))
; #define MMA(ai, bj, At_, Bt_) do { __builtin_amdgcn_s_setprio(1); \
;     _Pragma("unroll") for (int m = 0; m < 4; ++m) _Pragma("unroll") for (int n = 0; n < 2; ++n) _Pragma("unroll") for (int k = 0; k < 2; ++k) \
;       acc[ai][bj][m][n] = __builtin_amdgcn_mfma_f32_16x16x32_bf16(At_[m][k], Bt_[n][k], acc[ai][bj][m][n], 0, 0, 0); \
;     __builtin_amdgcn_s_setprio(0); } while (0)
; #define WAIT_V(n) asm volatile("s_waitcnt vmcnt(" #n ")" ::: "memory")
; #define WAIT_L(n) asm volatile("s_waitcnt lgkmcnt(" #n ")" ::: "memory")
; #define BAR __builtin_amdgcn_s_barrier()
; #define SCHED __builtin_amdgcn_sched_barrier(0)
; DI void gemm_tile(const GD& g, int pm, int pn, bf16_t* shm) {
;     ...
;   for (int t = 0; t < nt - 2; t += 2) {
;     LDB(B0, 0, 0); SCHED; LDA(At, 0, 0); STAGE(SA(1, 1), A, lda, brow + HALF, t + 1);
;     WAIT_L(8); BAR; WAIT_L(0); MMA(0, 0, At, B0); BAR; SCHED;
;     LDB(B1, 0, 1); STAGE(SB(0, 0), Bt, ldb, bh0, t + 2);
;     BAR; WAIT_L(0); MMA(0, 1, At, B1); BAR;
;     LDA(At, 0, 1); STAGE(SA(0, 0), A, lda, brow, t + 2);
;     BAR; WAIT_L(0); MMA(1, 0, At, B0); BAR; SCHED;
;     STAGE(SB(0, 1), Bt, ldb, bh1, t + 2);
;     WAIT_V(6); BAR; MMA(1, 1, At, B1); BAR;
	v_mov_b32_e32 v64, v2
	v_mov_b32_e32 v65, v2
	v_mov_b32_e32 v66, v2
	v_mov_b32_e32 v67, v2
	v_mov_b32_e32 v68, v2
	v_mov_b32_e32 v69, v2
	v_mov_b32_e32 v70, v2
	v_mov_b32_e32 v71, v2
	v_mov_b32_e32 v72, v2
	v_mov_b32_e32 v73, v2
	v_mov_b32_e32 v74, v2
	v_mov_b32_e32 v75, v2
	v_mov_b32_e32 v76, v2
	v_mov_b32_e32 v77, v2
	v_mov_b32_e32 v78, v2
	v_mov_b32_e32 v79, v2
	v_mov_b32_e32 v80, v2
	v_mov_b32_e32 v81, v2
	v_mov_b32_e32 v82, v2
	v_mov_b32_e32 v83, v2
	v_mov_b32_e32 v84, v2
	v_mov_b32_e32 v85, v2
	v_mov_b32_e32 v86, v2
	v_mov_b32_e32 v87, v2
	v_mov_b32_e32 v88, v2
	v_mov_b32_e32 v89, v2
	v_mov_b32_e32 v90, v2
	v_mov_b32_e32 v91, v2
	v_mov_b32_e32 v92, v2
	v_mov_b32_e32 v93, v2
	v_mov_b32_e32 v94, v2
	v_mov_b32_e32 v95, v2
	v_mov_b32_e32 v96, v2
	v_mov_b32_e32 v97, v2
	v_mov_b32_e32 v98, v2
	v_mov_b32_e32 v99, v2
	v_mov_b32_e32 v100, v2
	v_mov_b32_e32 v101, v2
	v_mov_b32_e32 v102, v2
	v_mov_b32_e32 v103, v2
	v_mov_b32_e32 v104, v2
	v_mov_b32_e32 v105, v2
	v_mov_b32_e32 v106, v2
	v_mov_b32_e32 v107, v2
	v_mov_b32_e32 v108, v2
	v_mov_b32_e32 v109, v2
	v_mov_b32_e32 v110, v2
	v_mov_b32_e32 v111, v2
	v_mov_b32_e32 v112, v2
	v_mov_b32_e32 v113, v2
	v_mov_b32_e32 v118, v2
	v_mov_b32_e32 v119, v2
	v_mov_b32_e32 v120, v2
	v_mov_b32_e32 v121, v2
	v_mov_b32_e32 v122, v2
	v_mov_b32_e32 v123, v2
	v_mov_b32_e32 v124, v2
	v_mov_b32_e32 v125, v2
	v_mov_b32_e32 v126, v2
	v_mov_b32_e32 v127, v2
	v_mov_b32_e32 v128, v2
	v_mov_b32_e32 v129, v2
	v_mov_b32_e32 v114, v2
	v_mov_b32_e32 v115, v2
	v_mov_b32_e32 v116, v2
	v_mov_b32_e32 v117, v2
	v_cmp_lt_u32_e32 vcc, 0xff, v130
	s_nop 1
	s_cbranch_vccz .Lgprio_skip
	s_setprio 1
.Lgprio_skip:
.LBB0_460:
	ds_read_b128 v[154:157], v147
	ds_read_b128 v[158:161], v147 offset:1024
	ds_read_b128 v[162:165], v147 offset:2048
	ds_read_b128 v[166:169], v147 offset:3072
	s_add_u32 s67, s41, 0xffffff00
	s_addc_u32 s97, s63, -1
	s_add_u32 s82, s67, s6
	s_addc_u32 s83, s97, s7
	s_add_i32 m0, s70, 0xc000
	v_lshl_add_u64 v[202:203], s[82:83], 0, v[0:1]
	s_add_u32 s82, s67, s8
	v_add_u32_e32 v237, v146, v142
	s_addc_u32 s83, s97, s9
	ds_read_b128 v[170:173], v237
	ds_read_b128 v[174:177], v237 offset:1024
	ds_read_b128 v[178:181], v148
	ds_read_b128 v[182:185], v148 offset:1024
	ds_read_b128 v[186:189], v149
	ds_read_b128 v[190:193], v149 offset:1024
	ds_read_b128 v[194:197], v150
	ds_read_b128 v[198:201], v150 offset:1024
	global_load_lds_dwordx4 v[202:203], off
	v_lshl_add_u64 v[202:203], s[82:83], 0, v[0:1]
	s_add_i32 m0, s70, 0xe000
	s_nop 0
	global_load_lds_dwordx4 v[202:203], off
	s_waitcnt lgkmcnt(8)
	s_barrier
	s_waitcnt lgkmcnt(0)
	s_waitcnt lgkmcnt(0)
	v_mfma_f32_16x16x32_bf16 v[114:117], v[170:173], v[154:157], v[114:117]
	v_mfma_f32_16x16x32_bf16 v[126:129], v[170:173], v[162:165], v[126:129]
	v_mfma_f32_16x16x32_bf16 v[122:125], v[178:181], v[154:157], v[122:125]
	v_mfma_f32_16x16x32_bf16 v[118:121], v[178:181], v[162:165], v[118:121]
	v_mfma_f32_16x16x32_bf16 v[110:113], v[186:189], v[154:157], v[110:113]
	v_mfma_f32_16x16x32_bf16 v[106:109], v[186:189], v[162:165], v[106:109]
	v_mfma_f32_16x16x32_bf16 v[102:105], v[194:197], v[154:157], v[102:105]
	v_mfma_f32_16x16x32_bf16 v[98:101], v[194:197], v[162:165], v[98:101]
	v_mfma_f32_16x16x32_bf16 v[114:117], v[174:177], v[158:161], v[114:117]
	v_mfma_f32_16x16x32_bf16 v[126:129], v[174:177], v[166:169], v[126:129]
	v_mfma_f32_16x16x32_bf16 v[122:125], v[182:185], v[158:161], v[122:125]
	v_mfma_f32_16x16x32_bf16 v[118:121], v[182:185], v[166:169], v[118:121]
	v_mfma_f32_16x16x32_bf16 v[110:113], v[190:193], v[158:161], v[110:113]
	v_mfma_f32_16x16x32_bf16 v[106:109], v[190:193], v[166:169], v[106:109]
	v_mfma_f32_16x16x32_bf16 v[102:105], v[198:201], v[158:161], v[102:105]
	v_mfma_f32_16x16x32_bf16 v[98:101], v[198:201], v[166:169], v[98:101]
	s_barrier
	s_add_i32 s3, s3, 2
	s_add_u32 s67, s58, 0xffffff80
	s_addc_u32 s97, s59, -1
	s_add_u32 s82, s67, s10
	s_addc_u32 s83, s97, s11
	v_lshl_add_u64 v[202:203], s[82:83], 0, v[0:1]
	s_add_u32 s82, s67, s12
	s_mov_b32 m0, s36
	s_addc_u32 s83, s97, s13
	ds_read_b128 v[238:241], v151
	ds_read_b128 v[242:245], v151 offset:1024
	ds_read_b128 v[246:249], v151 offset:2048
	ds_read_b128 v[214:217], v151 offset:3072
	global_load_lds_dwordx4 v[202:203], off
	v_lshl_add_u64 v[202:203], s[82:83], 0, v[0:1]
	s_mov_b32 m0, s66
	s_nop 0
	global_load_lds_dwordx4 v[202:203], off
	s_barrier
	s_waitcnt lgkmcnt(0)
	s_waitcnt lgkmcnt(0)
	v_mfma_f32_16x16x32_bf16 v[94:97], v[170:173], v[238:241], v[94:97]
	v_mfma_f32_16x16x32_bf16 v[90:93], v[170:173], v[246:249], v[90:93]
	v_mfma_f32_16x16x32_bf16 v[86:89], v[178:181], v[238:241], v[86:89]
	v_mfma_f32_16x16x32_bf16 v[82:85], v[178:181], v[246:249], v[82:85]
	v_mfma_f32_16x16x32_bf16 v[78:81], v[186:189], v[238:241], v[78:81]
	v_mfma_f32_16x16x32_bf16 v[74:77], v[186:189], v[246:249], v[74:77]
	v_mfma_f32_16x16x32_bf16 v[70:73], v[194:197], v[238:241], v[70:73]
	v_mfma_f32_16x16x32_bf16 v[66:69], v[194:197], v[246:249], v[66:69]
	v_mfma_f32_16x16x32_bf16 v[94:97], v[174:177], v[242:245], v[94:97]
	v_mfma_f32_16x16x32_bf16 v[90:93], v[174:177], v[214:217], v[90:93]
	v_mfma_f32_16x16x32_bf16 v[86:89], v[182:185], v[242:245], v[86:89]
	v_mfma_f32_16x16x32_bf16 v[82:85], v[182:185], v[214:217], v[82:85]
	v_mfma_f32_16x16x32_bf16 v[78:81], v[190:193], v[242:245], v[78:81]
	v_mfma_f32_16x16x32_bf16 v[74:77], v[190:193], v[214:217], v[74:77]
	v_mfma_f32_16x16x32_bf16 v[70:73], v[198:201], v[242:245], v[70:73]
	v_mfma_f32_16x16x32_bf16 v[66:69], v[198:201], v[214:217], v[66:69]
	s_add_u32 vcc_lo, s41, 0xffffff80
	s_addc_u32 vcc_hi, s63, -1
	s_add_u32 s82, vcc_lo, s50
	s_addc_u32 s83, vcc_hi, s51
	v_lshl_add_u64 v[202:203], s[82:83], 0, v[0:1]
	s_add_u32 s82, vcc_lo, s52
	s_mov_b32 m0, s70
	s_addc_u32 s83, vcc_hi, s53
	s_barrier
; #define LDA(dst, b, h) _Pragma("unroll") for (int m = 0; m < 4; ++m) _Pragma("unroll") for (int k = 0; k < 2; ++k) \
;     dst[m][k] = *reinterpret_cast<const bf16x8*>((char*)SA(b, h) + lds_byte(wr * 64 + m * 16 + fr, k * 32 + fq * 8))
; #define LDB(dst, b, h) _Pragma("unroll") for (int n = 0; n < 2; ++n) _Pragma("unroll") for (int k = 0; k < 2; ++k) \
;     dst[n][k] = *reinterpret_cast<const bf16x8*>((char*)SB(b, h) + lds_byte(wc * 32 + n * 16 + fr, k * 32 + fq * 8))
; #define MMA(ai, bj, At_, Bt_) do { __builtin_amdgcn_s_setprio(1); \
;     _Pragma("unroll") for (int m = 0; m < 4; ++m) _Pragma("unroll") for (int n = 0; n < 2; ++n) _Pragma("unroll") for (int k = 0; k < 2; ++k) \
;       acc[ai][bj][m][n] = __builtin_amdgcn_mfma_f32_16x16x32_bf16(At_[m][k], Bt_[n][k], acc[ai][bj][m][n], 0, 0, 0); \
;     __builtin_amdgcn_s_setprio(0); } while (0)
; #define WAIT_V(n) asm volatile("s_waitcnt vmcnt(" #n ")" ::: "memory")
; #define WAIT_L(n) asm volatile("s_waitcnt lgkmcnt(" #n ")" ::: "memory")
; #define BAR __builtin_amdgcn_s_barrier()
; #define SCHED __builtin_amdgcn_sched_barrier(0)
; DI void gemm_tile(const GD& g, int pm, int pn, bf16_t* shm) {
;     ...
;     LDA(At, 0, 1); STAGE(SA(0, 0), A, lda, brow, t + 2);
;     BAR; WAIT_L(0); MMA(1, 0, At, B0); BAR; SCHED;
;     STAGE(SB(0, 1), Bt, ldb, bh1, t + 2);
;     WAIT_V(6); BAR; MMA(1, 1, At, B1); BAR;
;     LDB(B0, 1, 0); SCHED; LDA(At, 1, 0); STAGE(SA(0, 1), A, lda, brow + HALF, t + 2);
;     WAIT_L(8); BAR; WAIT_L(0); MMA(0, 0, At, B0); BAR; SCHED;
;     LDB(B1, 1, 1); STAGE(SB(1, 0), Bt, ldb, bh0, t + 3);
;     BAR; WAIT_L(0); MMA(0, 1, At, B1); BAR;
;     LDA(At, 1, 1); STAGE(SA(1, 0), A, lda, brow, t + 3);
	ds_read_b128 v[170:173], v237 offset:16384
	ds_read_b128 v[174:177], v237 offset:17408
	ds_read_b128 v[178:181], v148 offset:16384
	ds_read_b128 v[182:185], v148 offset:17408
	ds_read_b128 v[186:189], v149 offset:16384
	ds_read_b128 v[190:193], v149 offset:17408
	ds_read_b128 v[194:197], v150 offset:16384
	ds_read_b128 v[198:201], v150 offset:17408
	global_load_lds_dwordx4 v[202:203], off
	v_lshl_add_u64 v[202:203], s[82:83], 0, v[0:1]
	s_mov_b32 m0, s44
	s_nop 0
	global_load_lds_dwordx4 v[202:203], off
	s_barrier
	s_waitcnt lgkmcnt(0)
	s_waitcnt lgkmcnt(0)
	v_mfma_f32_16x16x32_bf16 v[62:65], v[170:173], v[154:157], v[62:65]
	v_mfma_f32_16x16x32_bf16 v[58:61], v[170:173], v[162:165], v[58:61]
	v_mfma_f32_16x16x32_bf16 v[54:57], v[178:181], v[154:157], v[54:57]
	v_mfma_f32_16x16x32_bf16 v[50:53], v[178:181], v[162:165], v[50:53]
	v_mfma_f32_16x16x32_bf16 v[46:49], v[186:189], v[154:157], v[46:49]
	v_mfma_f32_16x16x32_bf16 v[42:45], v[186:189], v[162:165], v[42:45]
	v_mfma_f32_16x16x32_bf16 v[38:41], v[194:197], v[154:157], v[38:41]
	v_mfma_f32_16x16x32_bf16 v[34:37], v[194:197], v[162:165], v[34:37]
	v_mfma_f32_16x16x32_bf16 v[62:65], v[174:177], v[158:161], v[62:65]
	v_mfma_f32_16x16x32_bf16 v[58:61], v[174:177], v[166:169], v[58:61]
	v_mfma_f32_16x16x32_bf16 v[54:57], v[182:185], v[158:161], v[54:57]
	v_mfma_f32_16x16x32_bf16 v[50:53], v[182:185], v[166:169], v[50:53]
	v_mfma_f32_16x16x32_bf16 v[46:49], v[190:193], v[158:161], v[46:49]
	v_mfma_f32_16x16x32_bf16 v[42:45], v[190:193], v[166:169], v[42:45]
	v_mfma_f32_16x16x32_bf16 v[38:41], v[198:201], v[158:161], v[38:41]
	v_mfma_f32_16x16x32_bf16 v[34:37], v[198:201], v[166:169], v[34:37]
	s_barrier
	s_add_u32 s82, s67, s54
	s_addc_u32 s83, s97, s55
	v_lshl_add_u64 v[154:155], s[82:83], 0, v[0:1]
	s_add_u32 s82, s67, s56
	s_mov_b32 m0, s69
	s_addc_u32 s83, s97, s57
	global_load_lds_dwordx4 v[154:155], off
	v_lshl_add_u64 v[154:155], s[82:83], 0, v[0:1]
	s_mov_b32 m0, s77
	s_nop 0
	global_load_lds_dwordx4 v[154:155], off
	s_waitcnt vmcnt(6)
	s_barrier
	v_mfma_f32_16x16x32_bf16 v[30:33], v[170:173], v[238:241], v[30:33]
	v_mfma_f32_16x16x32_bf16 v[26:29], v[170:173], v[246:249], v[26:29]
	v_mfma_f32_16x16x32_bf16 v[22:25], v[178:181], v[238:241], v[22:25]
	v_mfma_f32_16x16x32_bf16 v[18:21], v[178:181], v[246:249], v[18:21]
	v_mfma_f32_16x16x32_bf16 v[14:17], v[186:189], v[238:241], v[14:17]
	v_mfma_f32_16x16x32_bf16 v[10:13], v[186:189], v[246:249], v[10:13]
	v_mfma_f32_16x16x32_bf16 v[6:9], v[194:197], v[238:241], v[6:9]
	v_mfma_f32_16x16x32_bf16 v[2:5], v[194:197], v[246:249], v[2:5]
	v_mfma_f32_16x16x32_bf16 v[30:33], v[174:177], v[242:245], v[30:33]
	v_mfma_f32_16x16x32_bf16 v[26:29], v[174:177], v[214:217], v[26:29]
	v_mfma_f32_16x16x32_bf16 v[22:25], v[182:185], v[242:245], v[22:25]
	v_mfma_f32_16x16x32_bf16 v[18:21], v[182:185], v[214:217], v[18:21]
	v_mfma_f32_16x16x32_bf16 v[14:17], v[190:193], v[242:245], v[14:17]
	v_mfma_f32_16x16x32_bf16 v[10:13], v[190:193], v[214:217], v[10:13]
	v_mfma_f32_16x16x32_bf16 v[6:9], v[198:201], v[242:245], v[6:9]
	v_mfma_f32_16x16x32_bf16 v[2:5], v[198:201], v[214:217], v[2:5]
	s_barrier
	ds_read_b128 v[154:157], v152
	ds_read_b128 v[158:161], v152 offset:1024
	ds_read_b128 v[162:165], v152 offset:2048
	ds_read_b128 v[166:169], v152 offset:3072
	s_add_u32 s82, vcc_lo, s6
	s_addc_u32 s83, vcc_hi, s7
	v_lshl_add_u64 v[202:203], s[82:83], 0, v[0:1]
	s_add_u32 s82, vcc_lo, s8
	s_mov_b32 m0, s71
	s_addc_u32 s83, vcc_hi, s9
	ds_read_b128 v[170:173], v237 offset:32768
	ds_read_b128 v[174:177], v237 offset:33792
	ds_read_b128 v[178:181], v148 offset:32768
	ds_read_b128 v[182:185], v148 offset:33792
	ds_read_b128 v[186:189], v149 offset:32768
	ds_read_b128 v[190:193], v149 offset:33792
	ds_read_b128 v[194:197], v150 offset:32768
	ds_read_b128 v[198:201], v150 offset:33792
	global_load_lds_dwordx4 v[202:203], off
	v_lshl_add_u64 v[202:203], s[82:83], 0, v[0:1]
	s_mov_b32 m0, s65
	s_nop 0
	global_load_lds_dwordx4 v[202:203], off
	s_waitcnt lgkmcnt(8)
	s_barrier
	s_waitcnt lgkmcnt(0)
	s_waitcnt lgkmcnt(0)
	v_mfma_f32_16x16x32_bf16 v[114:117], v[170:173], v[154:157], v[114:117]
	v_mfma_f32_16x16x32_bf16 v[126:129], v[170:173], v[162:165], v[126:129]
	v_mfma_f32_16x16x32_bf16 v[122:125], v[178:181], v[154:157], v[122:125]
	v_mfma_f32_16x16x32_bf16 v[118:121], v[178:181], v[162:165], v[118:121]
	v_mfma_f32_16x16x32_bf16 v[110:113], v[186:189], v[154:157], v[110:113]
	v_mfma_f32_16x16x32_bf16 v[106:109], v[186:189], v[162:165], v[106:109]
	v_mfma_f32_16x16x32_bf16 v[102:105], v[194:197], v[154:157], v[102:105]
	v_mfma_f32_16x16x32_bf16 v[98:101], v[194:197], v[162:165], v[98:101]
	v_mfma_f32_16x16x32_bf16 v[114:117], v[174:177], v[158:161], v[114:117]
	v_mfma_f32_16x16x32_bf16 v[126:129], v[174:177], v[166:169], v[126:129]
	v_mfma_f32_16x16x32_bf16 v[122:125], v[182:185], v[158:161], v[122:125]
	v_mfma_f32_16x16x32_bf16 v[118:121], v[182:185], v[166:169], v[118:121]
	v_mfma_f32_16x16x32_bf16 v[110:113], v[190:193], v[158:161], v[110:113]
	v_mfma_f32_16x16x32_bf16 v[106:109], v[190:193], v[166:169], v[106:109]
	v_mfma_f32_16x16x32_bf16 v[102:105], v[198:201], v[158:161], v[102:105]
	v_mfma_f32_16x16x32_bf16 v[98:101], v[198:201], v[166:169], v[98:101]
	s_barrier
	s_add_u32 s82, s58, s10
	s_addc_u32 s83, s59, s11
	v_lshl_add_u64 v[202:203], s[82:83], 0, v[0:1]
	s_add_u32 s82, s58, s12
	s_mov_b32 m0, s96
	s_addc_u32 s83, s59, s13
	ds_read_b128 v[214:217], v153
	ds_read_b128 v[238:241], v153 offset:1024
	ds_read_b128 v[242:245], v153 offset:2048
	ds_read_b128 v[246:249], v153 offset:3072
	global_load_lds_dwordx4 v[202:203], off
	v_lshl_add_u64 v[202:203], s[82:83], 0, v[0:1]
	s_mov_b32 m0, s60
	s_nop 0
	global_load_lds_dwordx4 v[202:203], off
	s_barrier
; #define LDA(dst, b, h) _Pragma("unroll") for (int m = 0; m < 4; ++m) _Pragma("unroll") for (int k = 0; k < 2; ++k) \
;     dst[m][k] = *reinterpret_cast<const bf16x8*>((char*)SA(b, h) + lds_byte(wr * 64 + m * 16 + fr, k * 32 + fq * 8))
; #define LDB(dst, b, h) _Pragma("unroll") for (int n = 0; n < 2; ++n) _Pragma("unroll") for (int k = 0; k < 2; ++k) \
;     dst[n][k] = *reinterpret_cast<const bf16x8*>((char*)SB(b, h) + lds_byte(wc * 32 + n * 16 + fr, k * 32 + fq * 8))
; #define MMA(ai, bj, At_, Bt_) do { __builtin_amdgcn_s_setprio(1); \
;     _Pragma("unroll") for (int m = 0; m < 4; ++m) _Pragma("unroll") for (int n = 0; n < 2; ++n) _Pragma("unroll") for (int k = 0; k < 2; ++k) \
;       acc[ai][bj][m][n] = __builtin_amdgcn_mfma_f32_16x16x32_bf16(At_[m][k], Bt_[n][k], acc[ai][bj][m][n], 0, 0, 0); \
;     __builtin_amdgcn_s_setprio(0); } while (0)
; #define WAIT_V(n) asm volatile("s_waitcnt vmcnt(" #n ")" ::: "memory")
; #define WAIT_L(n) asm volatile("s_waitcnt lgkmcnt(" #n ")" ::: "memory")
; #define BAR __builtin_amdgcn_s_barrier()
; #define SCHED __builtin_amdgcn_sched_barrier(0)
; DI void gemm_tile(const GD& g, int pm, int pn, bf16_t* shm) {
;     ...
;     LDB(B0, 1, 0); SCHED; LDA(At, 1, 0); STAGE(SA(0, 1), A, lda, brow + HALF, t + 2);
;     WAIT_L(8); BAR; WAIT_L(0); MMA(0, 0, At, B0); BAR; SCHED;
;     LDB(B1, 1, 1); STAGE(SB(1, 0), Bt, ldb, bh0, t + 3);
;     BAR; WAIT_L(0); MMA(0, 1, At, B1); BAR;
;     LDA(At, 1, 1); STAGE(SA(1, 0), A, lda, brow, t + 3);
;     BAR; WAIT_L(0); MMA(1, 0, At, B0); BAR; SCHED;
;     STAGE(SB(1, 1), Bt, ldb, bh1, t + 3);
;     WAIT_V(6); BAR; MMA(1, 1, At, B1); BAR;
;   }
	s_waitcnt lgkmcnt(0)
	s_waitcnt lgkmcnt(0)
	v_mfma_f32_16x16x32_bf16 v[94:97], v[170:173], v[214:217], v[94:97]
	v_mfma_f32_16x16x32_bf16 v[90:93], v[170:173], v[242:245], v[90:93]
	v_mfma_f32_16x16x32_bf16 v[86:89], v[178:181], v[214:217], v[86:89]
	v_mfma_f32_16x16x32_bf16 v[82:85], v[178:181], v[242:245], v[82:85]
	v_mfma_f32_16x16x32_bf16 v[78:81], v[186:189], v[214:217], v[78:81]
	v_mfma_f32_16x16x32_bf16 v[74:77], v[186:189], v[242:245], v[74:77]
	v_mfma_f32_16x16x32_bf16 v[70:73], v[194:197], v[214:217], v[70:73]
	v_mfma_f32_16x16x32_bf16 v[66:69], v[194:197], v[242:245], v[66:69]
	v_mfma_f32_16x16x32_bf16 v[94:97], v[174:177], v[238:241], v[94:97]
	v_mfma_f32_16x16x32_bf16 v[90:93], v[174:177], v[246:249], v[90:93]
	v_mfma_f32_16x16x32_bf16 v[86:89], v[182:185], v[238:241], v[86:89]
	v_mfma_f32_16x16x32_bf16 v[82:85], v[182:185], v[246:249], v[82:85]
	v_mfma_f32_16x16x32_bf16 v[78:81], v[190:193], v[238:241], v[78:81]
	v_mfma_f32_16x16x32_bf16 v[74:77], v[190:193], v[246:249], v[74:77]
	v_mfma_f32_16x16x32_bf16 v[70:73], v[198:201], v[238:241], v[70:73]
	v_mfma_f32_16x16x32_bf16 v[66:69], v[198:201], v[246:249], v[66:69]
	s_add_u32 s82, s41, s50
	s_addc_u32 s83, s63, s51
	v_lshl_add_u64 v[202:203], s[82:83], 0, v[0:1]
	s_add_u32 s82, s41, s52
	s_mov_b32 m0, s25
	s_addc_u32 s83, s63, s53
	s_barrier
	ds_read_b128 v[170:173], v237 offset:49152
	ds_read_b128 v[174:177], v237 offset:50176
	ds_read_b128 v[178:181], v148 offset:49152
	ds_read_b128 v[182:185], v148 offset:50176
	ds_read_b128 v[186:189], v149 offset:49152
	ds_read_b128 v[190:193], v149 offset:50176
	ds_read_b128 v[194:197], v150 offset:49152
	ds_read_b128 v[198:201], v150 offset:50176
	global_load_lds_dwordx4 v[202:203], off
	v_lshl_add_u64 v[202:203], s[82:83], 0, v[0:1]
	s_mov_b32 m0, s61
	s_nop 0
	global_load_lds_dwordx4 v[202:203], off
	s_barrier
	s_waitcnt lgkmcnt(0)
	s_waitcnt lgkmcnt(0)
	v_mfma_f32_16x16x32_bf16 v[62:65], v[170:173], v[154:157], v[62:65]
	v_mfma_f32_16x16x32_bf16 v[58:61], v[170:173], v[162:165], v[58:61]
	v_mfma_f32_16x16x32_bf16 v[54:57], v[178:181], v[154:157], v[54:57]
	v_mfma_f32_16x16x32_bf16 v[50:53], v[178:181], v[162:165], v[50:53]
	v_mfma_f32_16x16x32_bf16 v[46:49], v[186:189], v[154:157], v[46:49]
	v_mfma_f32_16x16x32_bf16 v[42:45], v[186:189], v[162:165], v[42:45]
	v_mfma_f32_16x16x32_bf16 v[38:41], v[194:197], v[154:157], v[38:41]
	v_mfma_f32_16x16x32_bf16 v[34:37], v[194:197], v[162:165], v[34:37]
	v_mfma_f32_16x16x32_bf16 v[62:65], v[174:177], v[158:161], v[62:65]
	v_mfma_f32_16x16x32_bf16 v[58:61], v[174:177], v[166:169], v[58:61]
	v_mfma_f32_16x16x32_bf16 v[54:57], v[182:185], v[158:161], v[54:57]
	v_mfma_f32_16x16x32_bf16 v[50:53], v[182:185], v[166:169], v[50:53]
	v_mfma_f32_16x16x32_bf16 v[46:49], v[190:193], v[158:161], v[46:49]
	v_mfma_f32_16x16x32_bf16 v[42:45], v[190:193], v[166:169], v[42:45]
	v_mfma_f32_16x16x32_bf16 v[38:41], v[198:201], v[158:161], v[38:41]
	v_mfma_f32_16x16x32_bf16 v[34:37], v[198:201], v[166:169], v[34:37]
	s_barrier
	s_add_u32 s82, s58, s54
	s_addc_u32 s83, s59, s55
	v_lshl_add_u64 v[154:155], s[82:83], 0, v[0:1]
	s_add_u32 s82, s58, s56
	s_mov_b32 m0, s62
	s_addc_u32 s83, s59, s57
	global_load_lds_dwordx4 v[154:155], off
	v_lshl_add_u64 v[154:155], s[82:83], 0, v[0:1]
	s_mov_b32 m0, s40
	s_nop 0
	global_load_lds_dwordx4 v[154:155], off
	s_waitcnt vmcnt(6)
	s_barrier
	v_mfma_f32_16x16x32_bf16 v[30:33], v[170:173], v[214:217], v[30:33]
	v_mfma_f32_16x16x32_bf16 v[26:29], v[170:173], v[242:245], v[26:29]
	v_mfma_f32_16x16x32_bf16 v[22:25], v[178:181], v[214:217], v[22:25]
	v_mfma_f32_16x16x32_bf16 v[18:21], v[178:181], v[242:245], v[18:21]
	v_mfma_f32_16x16x32_bf16 v[14:17], v[186:189], v[214:217], v[14:17]
	v_mfma_f32_16x16x32_bf16 v[10:13], v[186:189], v[242:245], v[10:13]
	v_mfma_f32_16x16x32_bf16 v[6:9], v[194:197], v[214:217], v[6:9]
	v_mfma_f32_16x16x32_bf16 v[2:5], v[194:197], v[242:245], v[2:5]
	v_mfma_f32_16x16x32_bf16 v[30:33], v[174:177], v[238:241], v[30:33]
	v_mfma_f32_16x16x32_bf16 v[26:29], v[174:177], v[246:249], v[26:29]
	v_mfma_f32_16x16x32_bf16 v[22:25], v[182:185], v[238:241], v[22:25]
	v_mfma_f32_16x16x32_bf16 v[18:21], v[182:185], v[246:249], v[18:21]
	v_mfma_f32_16x16x32_bf16 v[14:17], v[190:193], v[238:241], v[14:17]
	v_mfma_f32_16x16x32_bf16 v[10:13], v[190:193], v[246:249], v[10:13]
	v_mfma_f32_16x16x32_bf16 v[6:9], v[198:201], v[238:241], v[6:9]
	v_mfma_f32_16x16x32_bf16 v[2:5], v[198:201], v[246:249], v[2:5]
	s_add_u32 s58, s58, 0x100
	s_addc_u32 s59, s59, 0
	s_add_u32 s41, s41, 0x100
	s_addc_u32 s63, s63, 0
	s_cmp_lt_u32 s3, s2
	s_barrier
	s_cbranch_scc1 .LBB0_460
	v_mov_b32_e32 v146, v143
	v_mov_b32_e32 v147, v144
	v_mov_b32_e32 v148, v145
	v_mov_b32_e32 v149, v142
; #define LDA(dst, b, h) _Pragma("unroll") for (int m = 0; m < 4; ++m) _Pragma("unroll") for (int k = 0; k < 2; ++k) \
;     dst[m][k] = *reinterpret_cast<const bf16x8*>((char*)SA(b, h) + lds_byte(wr * 64 + m * 16 + fr, k * 32 + fq * 8))
; #define LDB(dst, b, h) _Pragma("unroll") for (int n = 0; n < 2; ++n) _Pragma("unroll") for (int k = 0; k < 2; ++k) \
;     dst[n][k] = *reinterpret_cast<const bf16x8*>((char*)SB(b, h) + lds_byte(wc * 32 + n * 16 + fr, k * 32 + fq * 8))
; #define MMA(ai, bj, At_, Bt_) do { __builtin_amdgcn_s_setprio(1); \
;     _Pragma("unroll") for (int m = 0; m < 4; ++m) _Pragma("unroll") for (int n = 0; n < 2; ++n) _Pragma("unroll") for (int k = 0; k < 2; ++k) \
;       acc[ai][bj][m][n] = __builtin_amdgcn_mfma_f32_16x16x32_bf16(At_[m][k], Bt_[n][k], acc[ai][bj][m][n], 0, 0, 0); \
;     __builtin_amdgcn_s_setprio(0); } while (0)
; #define WAIT_V(n) asm volatile("s_waitcnt vmcnt(" #n ")" ::: "memory")
; #define WAIT_L(n) asm volatile("s_waitcnt lgkmcnt(" #n ")" ::: "memory")
; #define BAR __builtin_amdgcn_s_barrier()
; DI void gemm_tile(const GD& g, int pm, int pn, bf16_t* shm) {
;     ...
;   { LDB(B0, 0, 0); LDA(At, 0, 0); STAGE(SA(1, 1), A, lda, brow + HALF, nt - 1);
;     BAR; WAIT_L(0); MMA(0, 0, At, B0); BAR;
;     LDB(B1, 0, 1); BAR; WAIT_L(0); MMA(0, 1, At, B1); BAR;
;     LDA(At, 0, 1); WAIT_V(4); BAR; WAIT_L(0); MMA(1, 0, At, B0); MMA(1, 1, At, B1); BAR; }
;   { LDB(B0, 1, 0); LDA(At, 1, 0); WAIT_V(2); BAR; WAIT_L(0); MMA(0, 0, At, B0); BAR;
;     LDB(B1, 1, 1); WAIT_V(0); BAR; WAIT_L(0); MMA(0, 1, At, B1); BAR;
;     LDA(At, 1, 1); BAR; WAIT_L(0); MMA(1, 0, At, B0); MMA(1, 1, At, B1); BAR; }
.LBB0_462:
	v_readlane_b32 s56, v253, 39
	v_readlane_b32 s57, v253, 40
	s_add_i32 s56, s24, -1
	s_lshl_b64 s[2:3], s[56:57], 7
	s_add_u32 s2, s0, s2
	v_add_u32_e32 v142, v141, v131
	v_add_u32_e32 v150, v141, v146
	v_add_u32_e32 v154, v141, v147
	v_add_u32_e32 v141, v141, v148
	s_addc_u32 s3, s1, s3
	ds_read_b128 v[142:145], v142
	ds_read_b128 v[150:153], v150
	ds_read_b128 v[154:157], v154
	ds_read_b128 v[158:161], v141
	v_add_u32_e32 v141, 0, v133
	s_add_u32 s0, s2, s6
	v_add_u32_e32 v203, v141, v134
	v_add_u32_e32 v134, 0, v133
	s_addc_u32 s1, s3, s7
	s_add_i32 m0, s70, 0xc000
	v_add_u32_e32 v214, v134, v135
	v_add_u32_e32 v215, v134, v136
	v_add_u32_e32 v134, 0, v133
	v_add_u32_e32 v133, 0, v133
	v_lshl_add_u64 v[186:187], s[0:1], 0, v[0:1]
	s_add_u32 s0, s2, s8
	v_add_u32_e32 v202, v141, v149
	v_add_u32_e32 v216, v134, v137
	v_add_u32_e32 v237, v133, v139
	s_addc_u32 s1, s3, s9
	ds_read_b128 v[162:165], v202
	ds_read_b128 v[166:169], v203
	ds_read_b128 v[170:173], v214
	ds_read_b128 v[174:177], v215
	v_add_u32_e32 v217, v134, v138
	ds_read_b128 v[134:137], v216
	ds_read_b128 v[178:181], v217
	v_add_u32_e32 v133, v133, v140
	ds_read_b128 v[138:141], v237
	ds_read_b128 v[182:185], v133
	global_load_lds_dwordx4 v[186:187], off
	v_lshl_add_u64 v[186:187], s[0:1], 0, v[0:1]
	s_add_i32 m0, s70, 0xe000
	s_nop 0
	global_load_lds_dwordx4 v[186:187], off
	s_barrier
	s_waitcnt lgkmcnt(0)
	s_waitcnt lgkmcnt(0)
	v_mfma_f32_16x16x32_bf16 v[114:117], v[162:165], v[142:145], v[114:117]
	v_mfma_f32_16x16x32_bf16 v[110:113], v[134:137], v[142:145], v[110:113]
	v_mfma_f32_16x16x32_bf16 v[106:109], v[134:137], v[154:157], v[106:109]
	v_mfma_f32_16x16x32_bf16 v[102:105], v[138:141], v[142:145], v[102:105]
	v_mfma_f32_16x16x32_bf16 v[98:101], v[138:141], v[154:157], v[98:101]
	v_mfma_f32_16x16x32_bf16 v[114:117], v[166:169], v[150:153], v[114:117]
	v_mfma_f32_16x16x32_bf16 v[126:129], v[162:165], v[154:157], v[126:129]
	v_mfma_f32_16x16x32_bf16 v[122:125], v[170:173], v[142:145], v[122:125]
	v_mfma_f32_16x16x32_bf16 v[118:121], v[170:173], v[154:157], v[118:121]
	v_mfma_f32_16x16x32_bf16 v[110:113], v[178:181], v[150:153], v[110:113]
	v_mfma_f32_16x16x32_bf16 v[106:109], v[178:181], v[158:161], v[106:109]
	v_mfma_f32_16x16x32_bf16 v[102:105], v[182:185], v[150:153], v[102:105]
	v_mfma_f32_16x16x32_bf16 v[98:101], v[182:185], v[158:161], v[98:101]
	v_mfma_f32_16x16x32_bf16 v[186:189], v[166:169], v[158:161], v[126:129]
	v_mfma_f32_16x16x32_bf16 v[190:193], v[174:177], v[150:153], v[122:125]
	v_mfma_f32_16x16x32_bf16 v[194:197], v[174:177], v[158:161], v[118:121]
	s_add_i32 s0, 0, 0x14000
	v_add_u32_e32 v0, s0, v132
	v_add_u32_e32 v118, v0, v131
	v_add_u32_e32 v122, v0, v146
	v_add_u32_e32 v126, v0, v147
	s_barrier
	ds_read_b128 v[118:121], v118
	ds_read_b128 v[122:125], v122
	v_add_u32_e32 v0, v0, v148
	ds_read_b128 v[126:129], v126
	ds_read_b128 v[198:201], v0
	s_barrier
	s_waitcnt lgkmcnt(0)
	s_waitcnt lgkmcnt(0)
	v_mfma_f32_16x16x32_bf16 v[94:97], v[162:165], v[118:121], v[94:97]
	v_mfma_f32_16x16x32_bf16 v[90:93], v[162:165], v[126:129], v[90:93]
	v_mfma_f32_16x16x32_bf16 v[86:89], v[170:173], v[118:121], v[86:89]
	v_mfma_f32_16x16x32_bf16 v[82:85], v[170:173], v[126:129], v[82:85]
	v_mfma_f32_16x16x32_bf16 v[78:81], v[134:137], v[118:121], v[78:81]
	v_mfma_f32_16x16x32_bf16 v[74:77], v[134:137], v[126:129], v[74:77]
	v_mfma_f32_16x16x32_bf16 v[70:73], v[138:141], v[118:121], v[70:73]
	v_mfma_f32_16x16x32_bf16 v[66:69], v[138:141], v[126:129], v[66:69]
	v_mfma_f32_16x16x32_bf16 v[94:97], v[166:169], v[122:125], v[94:97]
	v_mfma_f32_16x16x32_bf16 v[90:93], v[166:169], v[198:201], v[90:93]
	v_mfma_f32_16x16x32_bf16 v[86:89], v[174:177], v[122:125], v[86:89]
	v_mfma_f32_16x16x32_bf16 v[82:85], v[174:177], v[198:201], v[82:85]
	v_mfma_f32_16x16x32_bf16 v[78:81], v[178:181], v[122:125], v[78:81]
	v_mfma_f32_16x16x32_bf16 v[74:77], v[178:181], v[198:201], v[74:77]
	v_mfma_f32_16x16x32_bf16 v[70:73], v[182:185], v[122:125], v[70:73]
	v_mfma_f32_16x16x32_bf16 v[66:69], v[182:185], v[198:201], v[66:69]
	s_barrier
	ds_read_b128 v[134:137], v202 offset:16384
	ds_read_b128 v[138:141], v203 offset:16384
	ds_read_b128 v[162:165], v214 offset:16384
	ds_read_b128 v[166:169], v215 offset:16384
	ds_read_b128 v[170:173], v216 offset:16384
	ds_read_b128 v[174:177], v217 offset:16384
	ds_read_b128 v[178:181], v237 offset:16384
	ds_read_b128 v[182:185], v133 offset:16384
	s_waitcnt vmcnt(4)
	s_barrier
	s_waitcnt lgkmcnt(0)
	s_waitcnt lgkmcnt(0)
	v_mfma_f32_16x16x32_bf16 v[62:65], v[134:137], v[142:145], v[62:65]
	v_mfma_f32_16x16x32_bf16 v[58:61], v[134:137], v[154:157], v[58:61]
	v_mfma_f32_16x16x32_bf16 v[54:57], v[162:165], v[142:145], v[54:57]
	v_mfma_f32_16x16x32_bf16 v[50:53], v[162:165], v[154:157], v[50:53]
	v_mfma_f32_16x16x32_bf16 v[46:49], v[170:173], v[142:145], v[46:49]
	v_mfma_f32_16x16x32_bf16 v[42:45], v[170:173], v[154:157], v[42:45]
	v_mfma_f32_16x16x32_bf16 v[38:41], v[178:181], v[142:145], v[38:41]
	v_mfma_f32_16x16x32_bf16 v[34:37], v[178:181], v[154:157], v[34:37]
	v_mfma_f32_16x16x32_bf16 v[62:65], v[138:141], v[150:153], v[62:65]
	v_mfma_f32_16x16x32_bf16 v[58:61], v[138:141], v[158:161], v[58:61]
	v_mfma_f32_16x16x32_bf16 v[54:57], v[166:169], v[150:153], v[54:57]
	v_mfma_f32_16x16x32_bf16 v[50:53], v[166:169], v[158:161], v[50:53]
	v_mfma_f32_16x16x32_bf16 v[46:49], v[174:177], v[150:153], v[46:49]
	v_mfma_f32_16x16x32_bf16 v[42:45], v[174:177], v[158:161], v[42:45]
	v_mfma_f32_16x16x32_bf16 v[38:41], v[182:185], v[150:153], v[38:41]
	v_mfma_f32_16x16x32_bf16 v[34:37], v[182:185], v[158:161], v[34:37]
	v_mfma_f32_16x16x32_bf16 v[30:33], v[134:137], v[118:121], v[30:33]
	v_mfma_f32_16x16x32_bf16 v[26:29], v[134:137], v[126:129], v[26:29]
	v_mfma_f32_16x16x32_bf16 v[22:25], v[162:165], v[118:121], v[22:25]
	v_mfma_f32_16x16x32_bf16 v[18:21], v[162:165], v[126:129], v[18:21]
	v_mfma_f32_16x16x32_bf16 v[30:33], v[138:141], v[122:125], v[30:33]
	v_mfma_f32_16x16x32_bf16 v[26:29], v[138:141], v[198:201], v[26:29]
	v_mfma_f32_16x16x32_bf16 v[22:25], v[166:169], v[122:125], v[22:25]
	v_mfma_f32_16x16x32_bf16 v[18:21], v[166:169], v[198:201], v[18:21]
	v_mfma_f32_16x16x32_bf16 v[14:17], v[170:173], v[118:121], v[14:17]
	v_mfma_f32_16x16x32_bf16 v[10:13], v[170:173], v[126:129], v[10:13]
	v_mfma_f32_16x16x32_bf16 v[6:9], v[178:181], v[118:121], v[6:9]
	v_mfma_f32_16x16x32_bf16 v[2:5], v[178:181], v[126:129], v[2:5]
	v_mfma_f32_16x16x32_bf16 v[134:137], v[174:177], v[122:125], v[14:17]
	v_mfma_f32_16x16x32_bf16 v[138:141], v[174:177], v[198:201], v[10:13]
	v_mfma_f32_16x16x32_bf16 v[142:145], v[182:185], v[122:125], v[6:9]
	v_mfma_f32_16x16x32_bf16 v[150:153], v[182:185], v[198:201], v[2:5]
	s_add_i32 s0, 0, 0x18000
	v_add_u32_e32 v0, s0, v132
	s_nop 0
	v_add_u32_e32 v2, v0, v131
	s_barrier
; #define LDA(dst, b, h) _Pragma("unroll") for (int m = 0; m < 4; ++m) _Pragma("unroll") for (int k = 0; k < 2; ++k) \
;     dst[m][k] = *reinterpret_cast<const bf16x8*>((char*)SA(b, h) + lds_byte(wr * 64 + m * 16 + fr, k * 32 + fq * 8))
; #define LDB(dst, b, h) _Pragma("unroll") for (int n = 0; n < 2; ++n) _Pragma("unroll") for (int k = 0; k < 2; ++k) \
;     dst[n][k] = *reinterpret_cast<const bf16x8*>((char*)SB(b, h) + lds_byte(wc * 32 + n * 16 + fr, k * 32 + fq * 8))
; #define MMA(ai, bj, At_, Bt_) do { __builtin_amdgcn_s_setprio(1); \
;     _Pragma("unroll") for (int m = 0; m < 4; ++m) _Pragma("unroll") for (int n = 0; n < 2; ++n) _Pragma("unroll") for (int k = 0; k < 2; ++k) \
;       acc[ai][bj][m][n] = __builtin_amdgcn_mfma_f32_16x16x32_bf16(At_[m][k], Bt_[n][k], acc[ai][bj][m][n], 0, 0, 0); \
;     __builtin_amdgcn_s_setprio(0); } while (0)
; #define WAIT_V(n) asm volatile("s_waitcnt vmcnt(" #n ")" ::: "memory")
; #define WAIT_L(n) asm volatile("s_waitcnt lgkmcnt(" #n ")" ::: "memory")
; #define BAR __builtin_amdgcn_s_barrier()
; DI void gemm_tile(const GD& g, int pm, int pn, bf16_t* shm) {
;     ...
;     LDA(At, 0, 1); WAIT_V(4); BAR; WAIT_L(0); MMA(1, 0, At, B0); MMA(1, 1, At, B1); BAR; }
;   { LDB(B0, 1, 0); LDA(At, 1, 0); WAIT_V(2); BAR; WAIT_L(0); MMA(0, 0, At, B0); BAR;
;     LDB(B1, 1, 1); WAIT_V(0); BAR; WAIT_L(0); MMA(0, 1, At, B1); BAR;
;     LDA(At, 1, 1); BAR; WAIT_L(0); MMA(1, 0, At, B0); MMA(1, 1, At, B1); BAR; }
;   if (wr == 0) BAR;
;   __syncthreads();
	v_add_u32_e32 v3, v0, v146
	ds_read_b128 v[154:157], v2
	ds_read_b128 v[158:161], v3
	v_add_u32_e32 v2, v0, v147
	v_add_u32_e32 v0, v0, v148
	ds_read_b128 v[162:165], v2
	ds_read_b128 v[166:169], v0
	ds_read_b128 v[2:5], v202 offset:32768
	ds_read_b128 v[6:9], v203 offset:32768
	ds_read_b128 v[10:13], v214 offset:32768
	ds_read_b128 v[14:17], v215 offset:32768
	ds_read_b128 v[170:173], v216 offset:32768
	ds_read_b128 v[174:177], v217 offset:32768
	ds_read_b128 v[178:181], v237 offset:32768
	ds_read_b128 v[182:185], v133 offset:32768
	s_waitcnt vmcnt(2)
	s_barrier
	s_waitcnt lgkmcnt(0)
	s_waitcnt lgkmcnt(0)
	v_mfma_f32_16x16x32_bf16 v[114:117], v[2:5], v[154:157], v[114:117]
	v_mfma_f32_16x16x32_bf16 v[126:129], v[6:9], v[158:161], v[114:117]
	v_mfma_f32_16x16x32_bf16 v[114:117], v[2:5], v[162:165], v[186:189]
	v_mfma_f32_16x16x32_bf16 v[122:125], v[6:9], v[166:169], v[114:117]
	v_mfma_f32_16x16x32_bf16 v[114:117], v[10:13], v[154:157], v[190:193]
	v_mfma_f32_16x16x32_bf16 v[118:121], v[14:17], v[158:161], v[114:117]
	v_mfma_f32_16x16x32_bf16 v[114:117], v[10:13], v[162:165], v[194:197]
	v_mfma_f32_16x16x32_bf16 v[110:113], v[170:173], v[154:157], v[110:113]
	v_mfma_f32_16x16x32_bf16 v[106:109], v[170:173], v[162:165], v[106:109]
	v_mfma_f32_16x16x32_bf16 v[102:105], v[178:181], v[154:157], v[102:105]
	v_mfma_f32_16x16x32_bf16 v[98:101], v[178:181], v[162:165], v[98:101]
	v_mfma_f32_16x16x32_bf16 v[114:117], v[14:17], v[166:169], v[114:117]
	v_mfma_f32_16x16x32_bf16 v[110:113], v[174:177], v[158:161], v[110:113]
	v_mfma_f32_16x16x32_bf16 v[106:109], v[174:177], v[166:169], v[106:109]
	v_mfma_f32_16x16x32_bf16 v[102:105], v[182:185], v[158:161], v[102:105]
	v_mfma_f32_16x16x32_bf16 v[98:101], v[182:185], v[166:169], v[98:101]
	s_add_i32 s0, 0, 0x1c000
	v_add_u32_e32 v0, s0, v132
	v_add_u32_e32 v131, v0, v131
	s_barrier
	v_add_u32_e32 v132, v0, v146
	ds_read_b128 v[186:189], v131
	ds_read_b128 v[190:193], v132
	v_add_u32_e32 v131, v0, v147
	v_add_u32_e32 v0, v0, v148
	ds_read_b128 v[146:149], v131
	ds_read_b128 v[194:197], v0
	s_waitcnt vmcnt(0)
	s_barrier
	s_waitcnt lgkmcnt(0)
	s_waitcnt lgkmcnt(0)
	v_mfma_f32_16x16x32_bf16 v[94:97], v[2:5], v[186:189], v[94:97]
	v_mfma_f32_16x16x32_bf16 v[2:5], v[2:5], v[146:149], v[90:93]
	v_mfma_f32_16x16x32_bf16 v[90:93], v[6:9], v[194:197], v[2:5]
	v_mfma_f32_16x16x32_bf16 v[2:5], v[10:13], v[186:189], v[86:89]
	v_mfma_f32_16x16x32_bf16 v[86:89], v[14:17], v[190:193], v[2:5]
	v_mfma_f32_16x16x32_bf16 v[2:5], v[10:13], v[146:149], v[82:85]
	v_mfma_f32_16x16x32_bf16 v[82:85], v[14:17], v[194:197], v[2:5]
	v_mfma_f32_16x16x32_bf16 v[2:5], v[170:173], v[186:189], v[78:81]
	v_mfma_f32_16x16x32_bf16 v[14:17], v[174:177], v[190:193], v[2:5]
	v_mfma_f32_16x16x32_bf16 v[2:5], v[170:173], v[146:149], v[74:77]
	v_mfma_f32_16x16x32_bf16 v[10:13], v[174:177], v[194:197], v[2:5]
	v_mfma_f32_16x16x32_bf16 v[2:5], v[178:181], v[186:189], v[70:73]
	v_mfma_f32_16x16x32_bf16 v[94:97], v[6:9], v[190:193], v[94:97]
	v_mfma_f32_16x16x32_bf16 v[6:9], v[182:185], v[190:193], v[2:5]
	v_mfma_f32_16x16x32_bf16 v[2:5], v[178:181], v[146:149], v[66:69]
	v_mfma_f32_16x16x32_bf16 v[2:5], v[182:185], v[194:197], v[2:5]
	s_barrier
	ds_read_b128 v[170:173], v202 offset:49152
	ds_read_b128 v[174:177], v203 offset:49152
	ds_read_b128 v[178:181], v214 offset:49152
	ds_read_b128 v[182:185], v215 offset:49152
	ds_read_b128 v[198:201], v216 offset:49152
	ds_read_b128 v[214:217], v217 offset:49152
	ds_read_b128 v[238:241], v237 offset:49152
	ds_read_b128 v[242:245], v133 offset:49152
	s_barrier
	s_waitcnt lgkmcnt(0)
	s_waitcnt lgkmcnt(0)
	v_mfma_f32_16x16x32_bf16 v[62:65], v[170:173], v[154:157], v[62:65]
	v_mfma_f32_16x16x32_bf16 v[58:61], v[170:173], v[162:165], v[58:61]
	v_mfma_f32_16x16x32_bf16 v[54:57], v[178:181], v[154:157], v[54:57]
	v_mfma_f32_16x16x32_bf16 v[50:53], v[178:181], v[162:165], v[50:53]
	v_mfma_f32_16x16x32_bf16 v[46:49], v[198:201], v[154:157], v[46:49]
	v_mfma_f32_16x16x32_bf16 v[42:45], v[198:201], v[162:165], v[42:45]
	v_mfma_f32_16x16x32_bf16 v[38:41], v[238:241], v[154:157], v[38:41]
	v_mfma_f32_16x16x32_bf16 v[34:37], v[238:241], v[162:165], v[34:37]
	v_mfma_f32_16x16x32_bf16 v[78:81], v[174:177], v[158:161], v[62:65]
	v_mfma_f32_16x16x32_bf16 v[74:77], v[174:177], v[166:169], v[58:61]
	v_mfma_f32_16x16x32_bf16 v[70:73], v[182:185], v[158:161], v[54:57]
	v_mfma_f32_16x16x32_bf16 v[66:69], v[182:185], v[166:169], v[50:53]
	v_mfma_f32_16x16x32_bf16 v[62:65], v[214:217], v[158:161], v[46:49]
	v_mfma_f32_16x16x32_bf16 v[58:61], v[214:217], v[166:169], v[42:45]
	v_mfma_f32_16x16x32_bf16 v[54:57], v[242:245], v[158:161], v[38:41]
	v_mfma_f32_16x16x32_bf16 v[50:53], v[242:245], v[166:169], v[34:37]
	v_mfma_f32_16x16x32_bf16 v[18:21], v[178:181], v[146:149], v[18:21]
	v_mfma_f32_16x16x32_bf16 v[30:33], v[170:173], v[186:189], v[30:33]
	v_mfma_f32_16x16x32_bf16 v[34:37], v[182:185], v[194:197], v[18:21]
	v_mfma_f32_16x16x32_bf16 v[18:21], v[198:201], v[186:189], v[134:137]
	v_mfma_f32_16x16x32_bf16 v[46:49], v[174:177], v[190:193], v[30:33]
	v_mfma_f32_16x16x32_bf16 v[26:29], v[170:173], v[146:149], v[26:29]
	v_mfma_f32_16x16x32_bf16 v[30:33], v[214:217], v[190:193], v[18:21]
	v_mfma_f32_16x16x32_bf16 v[18:21], v[198:201], v[146:149], v[138:141]
	v_mfma_f32_16x16x32_bf16 v[42:45], v[174:177], v[194:197], v[26:29]
	v_mfma_f32_16x16x32_bf16 v[22:25], v[178:181], v[186:189], v[22:25]
	v_mfma_f32_16x16x32_bf16 v[26:29], v[214:217], v[194:197], v[18:21]
	v_mfma_f32_16x16x32_bf16 v[18:21], v[238:241], v[186:189], v[142:145]
	v_mfma_f32_16x16x32_bf16 v[38:41], v[182:185], v[190:193], v[22:25]
	v_mfma_f32_16x16x32_bf16 v[22:25], v[242:245], v[190:193], v[18:21]
	v_mfma_f32_16x16x32_bf16 v[18:21], v[238:241], v[146:149], v[150:153]
	v_mfma_f32_16x16x32_bf16 v[18:21], v[242:245], v[194:197], v[18:21]
	s_setprio 0
	s_movk_i32 s0, 0x100
	v_cmp_gt_u32_e32 vcc, s0, v130
	s_barrier
	s_and_saveexec_b64 s[0:1], vcc
	s_mov_b32 s96, s68
	s_mov_b32 s36, s89
	s_cbranch_execz .LBB0_464
	s_barrier
